# thr tile body: one indexer MFMA per eight accumulation fmas (cost-weighted spacing) instead of back-to-back dependent pairs; remaining LDS operand reads issued at tile top
# baseline (speedup 1.0000x reference)
; #define MFMA(a, b, c) __builtin_amdgcn_mfma_f32_32x32x16_bf16((a), (b), (c), 0, 0, 0)
; DI f32x16 zero16() { f32x16 z; for (int i = 0; i < 16; ++i) z[i] = 0.f; return z; }
; DI void dsa_thr_item(const Params& p, int b, int qblk, char* smem) {
;     ...
;     for (int kt = wave; kt <= qblk; kt += 8) {
;       const bf16x8 k0 = kn0, k1 = kn1;
;       {
;         const int ktn = min(kt + 8, qblk);
;         kn0 = ldg8(kib + (size_t)ktn * 1024); kn1 = ldg8(kib + (size_t)ktn * 1024 + 512);
;       }
;       float sc[16];
;       {
;         f32x16 a = zero16();
;         a = MFMA(k0, *reinterpret_cast<const bf16x8*>(qil + 256), a);
;         a = MFMA(k1, *reinterpret_cast<const bf16x8*>(qil + 256 + 16), a);
; #pragma unroll
;         for (int i = 0; i < 16; ++i) sc[i] = a[i];
;       }
; #pragma unroll
;       for (int hd = 0; hd < 8; ++hd) {
;         f32x16 a = zero16();
;         a = MFMA(k0, *reinterpret_cast<const bf16x8*>(qil + hd * 32), a);
;         a = MFMA(k1, *reinterpret_cast<const bf16x8*>(qil + hd * 32 + 16), a);
;         const float wh = wq[hd];
; #pragma unroll
;         for (int i = 0; i < 16; ++i) sc[i] = fmaf(fabsf(a[i]), wh, sc[i]);
;       }
.LBB0_268:
	v_mov_b32_e32 v97, v96
	v_add_u32_e32 v96, 8, v97
	v_min_i32_e32 v52, s71, v96
	v_lshlrev_b64 v[0:1], 11, v[52:53]
	s_waitcnt vmcnt(0)
	v_mov_b64_e32 v[42:43], v[38:39]
	s_waitcnt vmcnt(0)
	v_mov_b64_e32 v[46:47], v[34:35]
	v_lshl_add_u64 v[0:1], v[54:55], 0, v[0:1]
	v_mov_b64_e32 v[40:41], v[36:37]
	v_mov_b64_e32 v[44:45], v[32:33]
	global_load_dwordx4 v[32:35], v[0:1], off
	global_load_dwordx4 v[36:39], v[0:1], off offset:1024
	ds_read_b128 v[4:7], v216 offset:33632
	ds_read_b128 v[8:11], v216 offset:33664
	ds_read_b128 v[12:15], v216 offset:33696
	ds_read_b128 v[0:3], v216 offset:33728
	ds_read_b128 v[24:27], v216 offset:33760
	v_mfma_f32_32x32x16_bf16 v[104:119], v[44:47], v[184:187], 0
	v_mfma_f32_32x32x16_bf16 v[104:119], v[40:43], v[188:191], v[104:119]
	v_cmp_ne_u32_e64 s[0:1], s71, v97
	s_mov_b64 s[62:63], 0
	v_mfma_f32_32x32x16_bf16 v[120:135], v[44:47], v[192:195], 0
	v_mfma_f32_32x32x16_bf16 v[120:135], v[40:43], v[196:199], v[120:135]
	v_mfma_f32_32x32x16_bf16 v[136:151], v[44:47], v[200:203], 0
	s_nop 7
	v_mfma_f32_32x32x16_bf16 v[136:151], v[40:43], v[220:223], v[136:151]
	s_nop 1
	v_fma_f32 v152, |v120|, v79, v104
	v_fma_f32 v153, |v121|, v79, v105
	v_fma_f32 v154, |v122|, v79, v106
	v_fma_f32 v155, |v123|, v79, v107
	v_fma_f32 v156, |v124|, v79, v108
	v_fma_f32 v157, |v125|, v79, v109
	v_fma_f32 v158, |v126|, v79, v110
	v_fma_f32 v159, |v127|, v79, v111
	v_fma_f32 v160, |v128|, v79, v112
	v_fma_f32 v161, |v129|, v79, v113
	v_fma_f32 v98, |v130|, v79, v114
	v_fma_f32 v99, |v131|, v79, v115
	v_fma_f32 v100, |v132|, v79, v116
	v_fma_f32 v101, |v133|, v79, v117
	v_fma_f32 v102, |v134|, v79, v118
	v_fma_f32 v103, |v135|, v79, v119
	v_mfma_f32_32x32x16_bf16 v[104:119], v[44:47], v[224:227], 0
	v_mfma_f32_32x32x16_bf16 v[104:119], v[40:43], v[228:231], v[104:119]
	v_fma_f32 v152, |v136|, v80, v152
	v_fma_f32 v153, |v137|, v80, v153
	v_fma_f32 v154, |v138|, v80, v154
	v_fma_f32 v155, |v139|, v80, v155
	v_fma_f32 v156, |v140|, v80, v156
	v_fma_f32 v157, |v141|, v80, v157
	v_fma_f32 v158, |v142|, v80, v158
	v_fma_f32 v159, |v143|, v80, v159
	v_mfma_f32_32x32x16_bf16 v[120:135], v[44:47], v[232:235], 0
	v_fma_f32 v160, |v144|, v80, v160
	v_fma_f32 v161, |v145|, v80, v161
	v_fma_f32 v98, |v146|, v80, v98
	v_fma_f32 v99, |v147|, v80, v99
	v_fma_f32 v100, |v148|, v80, v100
	v_fma_f32 v101, |v149|, v80, v101
	v_fma_f32 v102, |v150|, v80, v102
	v_fma_f32 v103, |v151|, v80, v103
	v_mfma_f32_32x32x16_bf16 v[120:135], v[40:43], v[236:239], v[120:135]
	v_fma_f32 v152, |v104|, v81, v152
	v_fma_f32 v153, |v105|, v81, v153
	v_fma_f32 v154, |v106|, v81, v154
	v_fma_f32 v155, |v107|, v81, v155
	v_fma_f32 v156, |v108|, v81, v156
	v_fma_f32 v157, |v109|, v81, v157
	v_fma_f32 v158, |v110|, v81, v158
	v_fma_f32 v159, |v111|, v81, v159
	v_mfma_f32_32x32x16_bf16 v[136:151], v[44:47], v[240:243], 0
	v_fma_f32 v160, |v112|, v81, v160
	v_fma_f32 v161, |v113|, v81, v161
	v_fma_f32 v98, |v114|, v81, v98
	v_fma_f32 v99, |v115|, v81, v99
	v_fma_f32 v100, |v116|, v81, v100
	v_fma_f32 v101, |v117|, v81, v101
	v_fma_f32 v102, |v118|, v81, v102
	v_fma_f32 v103, |v119|, v81, v103
	v_mfma_f32_32x32x16_bf16 v[136:151], v[40:43], v[244:247], v[136:151]
	v_fma_f32 v152, |v120|, v82, v152
	v_fma_f32 v153, |v121|, v82, v153
	v_fma_f32 v154, |v122|, v82, v154
	v_fma_f32 v155, |v123|, v82, v155
	v_fma_f32 v156, |v124|, v82, v156
	v_fma_f32 v157, |v125|, v82, v157
	v_fma_f32 v158, |v126|, v82, v158
	v_fma_f32 v159, |v127|, v82, v159
	v_mfma_f32_32x32x16_bf16 v[104:119], v[44:47], v[248:251], 0
	v_fma_f32 v160, |v128|, v82, v160
	v_fma_f32 v161, |v129|, v82, v161
	v_fma_f32 v98, |v130|, v82, v98
	v_fma_f32 v99, |v131|, v82, v99
	v_fma_f32 v100, |v132|, v82, v100
	v_fma_f32 v101, |v133|, v82, v101
	v_fma_f32 v102, |v134|, v82, v102
	v_fma_f32 v103, |v135|, v82, v103
	s_waitcnt lgkmcnt(0)
	v_mfma_f32_32x32x16_bf16 v[104:119], v[40:43], v[4:7], v[104:119]
	v_fma_f32 v152, |v136|, v83, v152
	v_fma_f32 v153, |v137|, v83, v153
	v_fma_f32 v154, |v138|, v83, v154
	v_fma_f32 v155, |v139|, v83, v155
	v_fma_f32 v156, |v140|, v83, v156
	v_fma_f32 v157, |v141|, v83, v157
	v_fma_f32 v158, |v142|, v83, v158
	v_fma_f32 v159, |v143|, v83, v159
	v_mfma_f32_32x32x16_bf16 v[120:135], v[44:47], v[8:11], 0
	v_fma_f32 v160, |v144|, v83, v160
	v_fma_f32 v161, |v145|, v83, v161
	v_fma_f32 v98, |v146|, v83, v98
	v_fma_f32 v99, |v147|, v83, v99
	v_fma_f32 v100, |v148|, v83, v100
	v_fma_f32 v101, |v149|, v83, v101
	v_fma_f32 v102, |v150|, v83, v102
	v_fma_f32 v103, |v151|, v83, v103
	v_mfma_f32_32x32x16_bf16 v[120:135], v[40:43], v[12:15], v[120:135]
	v_fma_f32 v152, |v104|, v84, v152
	v_fma_f32 v153, |v105|, v84, v153
	v_fma_f32 v154, |v106|, v84, v154
	v_fma_f32 v155, |v107|, v84, v155
	v_fma_f32 v156, |v108|, v84, v156
	v_fma_f32 v157, |v109|, v84, v157
	v_fma_f32 v158, |v110|, v84, v158
	v_fma_f32 v159, |v111|, v84, v159
	v_mfma_f32_32x32x16_bf16 v[136:151], v[44:47], v[0:3], 0
	v_fma_f32 v160, |v112|, v84, v160
	v_fma_f32 v161, |v113|, v84, v161
	v_fma_f32 v98, |v114|, v84, v98
	v_fma_f32 v99, |v115|, v84, v99
	v_fma_f32 v100, |v116|, v84, v100
	v_fma_f32 v101, |v117|, v84, v101
	v_fma_f32 v102, |v118|, v84, v102
	v_fma_f32 v103, |v119|, v84, v103
	v_mfma_f32_32x32x16_bf16 v[136:151], v[40:43], v[24:27], v[136:151]
	v_fma_f32 v152, |v120|, v85, v152
	v_fma_f32 v153, |v121|, v85, v153
	v_fma_f32 v154, |v122|, v85, v154
	v_fma_f32 v155, |v123|, v85, v155
	v_fma_f32 v156, |v124|, v85, v156
	v_fma_f32 v157, |v125|, v85, v157
	v_fma_f32 v158, |v126|, v85, v158
	v_fma_f32 v159, |v127|, v85, v159
	v_fma_f32 v160, |v128|, v85, v160
	v_fma_f32 v161, |v129|, v85, v161
	v_fma_f32 v98, |v130|, v85, v98
	v_fma_f32 v99, |v131|, v85, v99
	v_fma_f32 v100, |v132|, v85, v100
	v_fma_f32 v101, |v133|, v85, v101
	v_fma_f32 v102, |v134|, v85, v102
	v_fma_f32 v103, |v135|, v85, v103
	v_fma_f32 v40, |v136|, v86, v152
	v_fma_f32 v22, |v137|, v86, v153
	v_fma_f32 v21, |v138|, v86, v154
	v_fma_f32 v20, |v139|, v86, v155
	v_fma_f32 v19, |v140|, v86, v156
	v_fma_f32 v18, |v141|, v86, v157
	v_fma_f32 v17, |v142|, v86, v158
	v_fma_f32 v16, |v143|, v86, v159
	v_fma_f32 v7, |v144|, v86, v160
	v_fma_f32 v6, |v145|, v86, v161
	v_fma_f32 v5, |v146|, v86, v98
	v_fma_f32 v4, |v147|, v86, v99
	v_fma_f32 v3, |v148|, v86, v100
	v_fma_f32 v2, |v149|, v86, v101
	v_fma_f32 v1, |v150|, v86, v102
	v_fma_f32 v0, |v151|, v86, v103
	v_ashrrev_i32_e32 v8, 31, v40
	v_bitop3_b32 v8, v8, v40, s67 bitop3:0x36
	v_lshrrev_b32_e32 v9, s58, v8
	v_lshrrev_b32_e32 v8, 8, v9
	v_cmp_eq_u32_e64 s[52:53], v8, v94
	s_and_saveexec_b64 s[64:65], s[0:1]
	s_xor_b64 s[64:65], exec, s[64:65]
	s_cbranch_execnz .LBB0_271
	s_andn2_saveexec_b64 s[64:65], s[64:65]
	s_cbranch_execnz .LBB0_302
